# v12 plus mla_norms gain vectors loaded once before the row loop
# baseline (speedup 1.0000x reference)
.LBB0_442:
	s_or_b64 exec, exec, s[4:5]
	v_mov_b32_e32 v1, v188
	v_mov_b32_e32 v2, 0x21d28
	s_waitcnt lgkmcnt(0)
	s_barrier
	v_readlane_b32 s4, v238, 7
	v_add_u32_e32 v2, 0, v2
	ds_read_b64 v[2:3], v2
	v_ashrrev_i32_e32 v0, 6, v1
	v_add_u32_e32 v32, s4, v0
	s_mov_b32 s4, 0xa800
	v_cmp_gt_i32_e32 vcc, s4, v32
	s_waitcnt lgkmcnt(0)
	v_readfirstlane_b32 s1, v2
	v_mov_b32_e32 v2, 0x21d28
	v_readfirstlane_b32 s0, v3
	v_add_u32_e32 v2, 0, v2
	ds_read_b64 v[2:3], v2
	s_waitcnt lgkmcnt(0)
	v_readfirstlane_b32 s12, v2
	v_mov_b32_e32 v2, 0x21d28
	v_readfirstlane_b32 s13, v3
	v_add_u32_e32 v2, 0, v2
	ds_read_b64 v[2:3], v2
	s_waitcnt lgkmcnt(0)
	v_readfirstlane_b32 s14, v2
	v_mov_b32_e32 v2, 0x21d28
	v_readfirstlane_b32 s15, v3
	v_add_u32_e32 v2, 0, v2
	ds_read_b64 v[2:3], v2
	s_waitcnt lgkmcnt(0)
	v_readfirstlane_b32 s16, v2
	v_mov_b32_e32 v2, 0x21d20
	v_readfirstlane_b32 s17, v3
	v_add_u32_e32 v2, 0, v2
	ds_read_b64 v[2:3], v2
	s_waitcnt lgkmcnt(0)
	v_readfirstlane_b32 s10, v2
	v_mov_b32_e32 v2, 0x21cc0
	v_readfirstlane_b32 s6, v3
	v_add_u32_e32 v2, 0, v2
	ds_read_b64 v[2:3], v2
	s_waitcnt lgkmcnt(0)
	v_readfirstlane_b32 s7, v2
	v_mov_b32_e32 v2, 0x21cd8
	v_readfirstlane_b32 s2, v3
	v_add_u32_e32 v2, 0, v2
	ds_read_b64 v[2:3], v2
	s_waitcnt lgkmcnt(0)
	v_readfirstlane_b32 s20, v3
	v_readfirstlane_b32 s21, v2
	s_and_saveexec_b64 s[4:5], vcc
	s_cbranch_execz .LBB0_466
	s_add_u32 s8, s1, 0xb078000
	s_addc_u32 s9, s0, 0
	s_add_u32 s10, s10, 0xa000000
	s_addc_u32 s11, s6, 0
	s_lshl_b32 s48, s58, 8
	s_lshl_b64 s[0:1], s[48:49], 2
	s_add_u32 s0, s21, s0
	s_addc_u32 s1, s20, s1
	s_lshl_b32 s48, s58, 9
	s_lshl_b64 s[20:21], s[48:49], 2
	v_and_b32_e32 v1, 63, v1
	s_add_u32 s6, s7, s20
	v_lshlrev_b32_e32 v12, 3, v1
	v_mov_b32_e32 v13, v165
	s_addc_u32 s7, s2, s21
	v_lshl_add_u64 v[2:3], s[14:15], 0, v[12:13]
	s_mov_b64 s[14:15], 0x8878000
	v_lshlrev_b32_e32 v164, 5, v1
	v_lshl_add_u64 v[16:17], v[2:3], 0, s[14:15]
	v_lshl_add_u64 v[2:3], s[16:17], 0, v[12:13]
	s_mov_b64 s[14:15], 0x5b38000
	v_lshl_add_u64 v[20:21], s[6:7], 0, v[164:165]
	v_lshlrev_b32_e32 v164, 4, v1
	v_lshlrev_b32_e32 v14, 2, v1
	v_lshl_add_u64 v[18:19], v[2:3], 0, s[14:15]
	v_lshl_add_u64 v[2:3], s[12:13], 0, v[164:165]
	s_mov_b64 s[6:7], 0x6078000
	v_lshl_add_u64 v[24:25], s[0:1], 0, v[164:165]
	v_readlane_b32 s0, v238, 52
	v_cmp_gt_u32_e32 vcc, 16, v1
	v_xor_b32_e32 v13, 0x80, v14
	v_lshl_add_u64 v[22:23], v[2:3], 0, s[6:7]
	v_lshl_add_u32 v15, v0, 8, s0
	s_mov_b64 s[12:13], 0
	global_load_dwordx4 v[226:229], v[20:21], off
	global_load_dwordx4 v[230:233], v[20:21], off offset:16
	global_load_dwordx4 v[240:243], v[24:25], off
	s_waitcnt vmcnt(0)
	s_branch .LBB0_446

.LBB0_457:
	s_waitcnt vmcnt(1)
	v_and_b32_e32 v33, 0xffff0000, v0
	v_lshlrev_b32_e32 v31, 16, v0
	v_mul_f32_e32 v10, v33, v33
	v_lshlrev_b32_e32 v42, 16, v1
	v_fmac_f32_e32 v10, v31, v31
	v_and_b32_e32 v43, 0xffff0000, v1
	v_and_b32_e32 v38, 0xffff0000, v2
	v_lshlrev_b32_e32 v39, 16, v2
	v_fmac_f32_e32 v10, v42, v42
	v_fmac_f32_e32 v10, v43, v43
	v_pk_mul_f32 v[8:9], v[38:39], v[38:39]
	v_and_b32_e32 v40, 0xffff0000, v3
	v_lshlrev_b32_e32 v41, 16, v3
	v_add_f32_e32 v9, v9, v10
	v_add_f32_e32 v10, v8, v9
	v_pk_mul_f32 v[8:9], v[40:41], v[40:41]
	s_mov_b32 s0, 0x800000
	v_add_f32_e32 v9, v9, v10
	v_add_f32_e32 v8, v8, v9
	ds_bpermute_b32 v9, v13, v8
	s_mov_b32 s28, 0x800000
	s_waitcnt lgkmcnt(0)
	v_add_f32_e32 v8, v8, v9
	ds_swizzle_b32 v9, v8 offset:swizzle(SWAP,16)
	s_waitcnt lgkmcnt(0)
	v_add_f32_e32 v8, v8, v9
	ds_swizzle_b32 v9, v8 offset:swizzle(SWAP,8)
	s_waitcnt lgkmcnt(0)
	v_add_f32_e32 v8, v8, v9
	ds_swizzle_b32 v9, v8 offset:swizzle(SWAP,4)
	s_waitcnt lgkmcnt(0)
	v_add_f32_e32 v8, v8, v9
	ds_swizzle_b32 v9, v8 offset:swizzle(SWAP,2)
	s_waitcnt lgkmcnt(0)
	v_add_f32_e32 v8, v8, v9
	ds_swizzle_b32 v9, v8 offset:swizzle(SWAP,1)
	s_waitcnt lgkmcnt(0)
	v_add_f32_e32 v8, v8, v9
	v_fmamk_f32 v8, v8, 0x3b000000, v189
	v_cmp_gt_f32_e64 s[38:39], s0, v8
	v_mul_f32_e32 v9, 0x4b800000, v8
	s_nop 0
	v_cndmask_b32_e64 v8, v8, v9, s[38:39]
	v_rsq_f32_e32 v8, v8
	s_nop 0
	v_mul_f32_e32 v9, 0x45800000, v8
	v_cndmask_b32_e64 v44, v8, v9, s[38:39]
	v_mov_b32_e32 v34, v230
	v_mov_b32_e32 v35, v231
	v_mov_b32_e32 v36, v232
	v_mov_b32_e32 v37, v233
	v_mov_b32_e32 v8, v226
	v_mov_b32_e32 v9, v227
	v_mov_b32_e32 v10, v228
	v_mov_b32_e32 v11, v229
	v_mul_f32_e32 v31, v44, v31
	s_waitcnt vmcnt(0)
	v_mul_f32_e32 v8, v8, v31
	v_mul_f32_e32 v31, v44, v33
	v_mul_f32_e32 v9, v9, v31
	v_cvt_pk_bf16_f32 v8, v8, v9
	v_mul_f32_e32 v9, v44, v42
	v_mul_f32_e32 v9, v10, v9
	v_mul_f32_e32 v10, v44, v43
	v_mul_f32_e32 v10, v11, v10
	v_cvt_pk_bf16_f32 v9, v9, v10
	v_mul_f32_e32 v10, v44, v39
	v_mul_f32_e32 v11, v44, v38
	v_mul_f32_e32 v10, v34, v10
	v_mul_f32_e32 v11, v35, v11
	v_ashrrev_i32_e32 v33, 31, v32
	v_cvt_pk_bf16_f32 v10, v10, v11
	v_mul_f32_e32 v11, v44, v41
	v_lshlrev_b64 v[34:35], 10, v[32:33]
	v_mul_f32_e32 v11, v36, v11
	v_mul_f32_e32 v31, v44, v40
	v_lshl_add_u64 v[34:35], v[22:23], 0, v[34:35]
	v_mul_f32_e32 v31, v37, v31
	v_cvt_pk_bf16_f32 v11, v11, v31
	global_store_dwordx4 v[34:35], v[8:11], off
	s_nop 1
	v_mov_b32_e32 v8, v240
	v_mov_b32_e32 v9, v241
	v_mov_b32_e32 v10, v242
	v_mov_b32_e32 v11, v243
	v_lshlrev_b32_e32 v34, 16, v28
	v_and_b32_e32 v35, 0xffff0000, v28
	v_lshlrev_b32_e32 v36, 16, v29
	v_and_b32_e32 v37, 0xffff0000, v29
	v_pk_mul_f32 v[38:39], v[34:35], v[34:35]
	v_pk_mul_f32 v[40:41], v[36:37], v[36:37]
	v_add_f32_e32 v31, v38, v39
	v_add_f32_e32 v31, v31, v40
	v_add_f32_e32 v31, v41, v31
	ds_bpermute_b32 v38, v13, v31
	s_waitcnt lgkmcnt(0)
	v_add_f32_e32 v31, v31, v38
	ds_swizzle_b32 v38, v31 offset:swizzle(SWAP,16)
	s_waitcnt lgkmcnt(0)
	v_add_f32_e32 v31, v31, v38
	ds_swizzle_b32 v38, v31 offset:swizzle(SWAP,8)
	s_waitcnt lgkmcnt(0)
	v_add_f32_e32 v31, v31, v38
	ds_swizzle_b32 v38, v31 offset:swizzle(SWAP,4)
	s_waitcnt lgkmcnt(0)
	v_add_f32_e32 v31, v31, v38
	ds_swizzle_b32 v38, v31 offset:swizzle(SWAP,2)
	s_waitcnt lgkmcnt(0)
	v_add_f32_e32 v31, v31, v38
	ds_swizzle_b32 v38, v31 offset:swizzle(SWAP,1)
	s_waitcnt lgkmcnt(0)
	v_add_f32_e32 v31, v31, v38
	v_fmamk_f32 v31, v31, 0x3b800000, v189
	v_cmp_gt_f32_e64 s[38:39], s0, v31
	v_mul_f32_e32 v38, 0x4b800000, v31
	s_movk_i32 s0, 0x2000
	v_cndmask_b32_e64 v31, v31, v38, s[38:39]
	v_rsq_f32_e32 v31, v31
	s_nop 0
	v_mul_f32_e32 v38, 0x45800000, v31
	v_cndmask_b32_e64 v38, v31, v38, s[38:39]
	v_pk_mul_f32 v[34:35], v[38:39], v[34:35] op_sel_hi:[0,1]
	v_cmp_gt_i32_e64 s[38:39], s0, v32
	v_pk_mul_f32 v[8:9], v[8:9], v[34:35]
	v_pk_mul_f32 v[34:35], v[38:39], v[36:37] op_sel_hi:[0,1]
	v_lshlrev_b64 v[36:37], 9, v[32:33]
	v_pk_mul_f32 v[10:11], v[10:11], v[34:35]
	v_lshl_add_u64 v[36:37], v[16:17], 0, v[36:37]
	v_cvt_pk_bf16_f32 v34, v8, v9
	v_cvt_pk_bf16_f32 v35, v10, v11
	global_store_dwordx2 v[36:37], v[34:35], off
	s_and_saveexec_b64 s[6:7], s[38:39]
	s_cbranch_execz .LBB0_459
	v_ashrrev_i32_e32 v31, 7, v32
	v_and_or_b32 v32, v31, -2, s58
	v_ashrrev_i32_e32 v33, 31, v32
	v_and_b32_e32 v31, 0xff00, v15
	v_lshlrev_b64 v[32:33], 18, v[32:33]
	v_lshl_add_u64 v[32:33], s[10:11], 0, v[32:33]
	v_lshlrev_b32_e32 v164, 2, v31
	v_lshl_add_u64 v[32:33], v[32:33], 0, v[164:165]
	v_lshlrev_b32_e32 v164, 2, v14
	v_lshl_add_u64 v[32:33], v[32:33], 0, v[164:165]
	global_store_dwordx4 v[32:33], v[8:11], off

.LBB0_464:
	s_waitcnt vmcnt(1)
	v_and_b32_e32 v40, 0xffff0000, v4
	v_lshlrev_b32_e32 v31, 16, v4
	v_mul_f32_e32 v10, v40, v40
	v_lshlrev_b32_e32 v41, 16, v5
	v_fmac_f32_e32 v10, v31, v31
	v_and_b32_e32 v42, 0xffff0000, v5
	v_and_b32_e32 v36, 0xffff0000, v6
	v_lshlrev_b32_e32 v37, 16, v6
	v_fmac_f32_e32 v10, v41, v41
	v_fmac_f32_e32 v10, v42, v42
	v_pk_mul_f32 v[8:9], v[36:37], v[36:37]
	v_and_b32_e32 v38, 0xffff0000, v7
	v_lshlrev_b32_e32 v39, 16, v7
	v_add_f32_e32 v9, v9, v10
	v_add_f32_e32 v10, v8, v9
	v_pk_mul_f32 v[8:9], v[38:39], v[38:39]
	s_mov_b32 s0, 0x800000
	v_add_f32_e32 v9, v9, v10
	v_add_f32_e32 v8, v8, v9
	ds_bpermute_b32 v9, v13, v8
	s_mov_b32 s28, 0x800000
	s_waitcnt lgkmcnt(0)
	v_add_f32_e32 v8, v8, v9
	ds_swizzle_b32 v9, v8 offset:swizzle(SWAP,16)
	s_waitcnt lgkmcnt(0)
	v_add_f32_e32 v8, v8, v9
	ds_swizzle_b32 v9, v8 offset:swizzle(SWAP,8)
	s_waitcnt lgkmcnt(0)
	v_add_f32_e32 v8, v8, v9
	ds_swizzle_b32 v9, v8 offset:swizzle(SWAP,4)
	s_waitcnt lgkmcnt(0)
	v_add_f32_e32 v8, v8, v9
	ds_swizzle_b32 v9, v8 offset:swizzle(SWAP,2)
	s_waitcnt lgkmcnt(0)
	v_add_f32_e32 v8, v8, v9
	ds_swizzle_b32 v9, v8 offset:swizzle(SWAP,1)
	s_waitcnt lgkmcnt(0)
	v_add_f32_e32 v8, v8, v9
	v_fmamk_f32 v8, v8, 0x3b000000, v189
	v_cmp_gt_f32_e64 s[36:37], s0, v8
	v_mul_f32_e32 v9, 0x4b800000, v8
	s_nop 0
	v_cndmask_b32_e64 v8, v8, v9, s[36:37]
	v_rsq_f32_e32 v8, v8
	s_nop 0
	v_mul_f32_e32 v9, 0x45800000, v8
	v_cndmask_b32_e64 v43, v8, v9, s[36:37]
	v_mov_b32_e32 v32, v230
	v_mov_b32_e32 v33, v231
	v_mov_b32_e32 v34, v232
	v_mov_b32_e32 v35, v233
	v_mov_b32_e32 v8, v226
	v_mov_b32_e32 v9, v227
	v_mov_b32_e32 v10, v228
	v_mov_b32_e32 v11, v229
	v_mul_f32_e32 v31, v43, v31
	s_waitcnt vmcnt(0)
	v_mul_f32_e32 v8, v8, v31
	v_mul_f32_e32 v31, v43, v40
	v_mul_f32_e32 v9, v9, v31
	v_cvt_pk_bf16_f32 v8, v8, v9
	v_mul_f32_e32 v9, v43, v41
	v_mul_f32_e32 v9, v10, v9
	v_mul_f32_e32 v10, v43, v42
	v_mul_f32_e32 v10, v11, v10
	v_cvt_pk_bf16_f32 v9, v9, v10
	v_mul_f32_e32 v10, v43, v37
	v_mul_f32_e32 v11, v43, v36
	v_mul_f32_e32 v10, v32, v10
	v_mul_f32_e32 v11, v33, v11
	v_cvt_pk_bf16_f32 v10, v10, v11
	v_mul_f32_e32 v11, v43, v39
	v_mul_f32_e32 v31, v43, v38
	v_mul_f32_e32 v11, v34, v11
	v_mul_f32_e32 v31, v35, v31
	v_cvt_pk_bf16_f32 v11, v11, v31
	v_ashrrev_i32_e32 v31, 31, v30
	v_lshlrev_b64 v[32:33], 10, v[30:31]
	v_lshl_add_u64 v[32:33], v[22:23], 0, v[32:33]
	global_store_dwordx4 v[32:33], v[8:11], off
	s_nop 1
	v_mov_b32_e32 v8, v240
	v_mov_b32_e32 v9, v241
	v_mov_b32_e32 v10, v242
	v_mov_b32_e32 v11, v243
	v_lshlrev_b32_e32 v32, 16, v26
	v_and_b32_e32 v33, 0xffff0000, v26
	v_lshlrev_b32_e32 v34, 16, v27
	v_and_b32_e32 v35, 0xffff0000, v27
	v_pk_mul_f32 v[36:37], v[32:33], v[32:33]
	v_pk_mul_f32 v[38:39], v[34:35], v[34:35]
	v_add_f32_e32 v36, v36, v37
	v_add_f32_e32 v36, v36, v38
	v_add_f32_e32 v36, v39, v36
	ds_bpermute_b32 v37, v13, v36
	s_waitcnt lgkmcnt(0)
	v_add_f32_e32 v36, v36, v37
	ds_swizzle_b32 v37, v36 offset:swizzle(SWAP,16)
	s_waitcnt lgkmcnt(0)
	v_add_f32_e32 v36, v36, v37
	ds_swizzle_b32 v37, v36 offset:swizzle(SWAP,8)
	s_waitcnt lgkmcnt(0)
	v_add_f32_e32 v36, v36, v37
	ds_swizzle_b32 v37, v36 offset:swizzle(SWAP,4)
	s_waitcnt lgkmcnt(0)
	v_add_f32_e32 v36, v36, v37
	ds_swizzle_b32 v37, v36 offset:swizzle(SWAP,2)
	s_waitcnt lgkmcnt(0)
	v_add_f32_e32 v36, v36, v37
	ds_swizzle_b32 v37, v36 offset:swizzle(SWAP,1)
	s_waitcnt lgkmcnt(0)
	v_add_f32_e32 v36, v36, v37
	v_fmamk_f32 v36, v36, 0x3b800000, v189
	v_cmp_gt_f32_e64 s[36:37], s0, v36
	v_mul_f32_e32 v37, 0x4b800000, v36
	s_movk_i32 s0, 0x2000
	v_cndmask_b32_e64 v36, v36, v37, s[36:37]
	v_rsq_f32_e32 v36, v36
	s_nop 0
	v_mul_f32_e32 v37, 0x45800000, v36
	v_cndmask_b32_e64 v36, v36, v37, s[36:37]
	v_pk_mul_f32 v[32:33], v[36:37], v[32:33] op_sel_hi:[0,1]
	v_cmp_gt_i32_e64 s[36:37], s0, v30
	v_pk_mul_f32 v[8:9], v[8:9], v[32:33]
	v_pk_mul_f32 v[32:33], v[36:37], v[34:35] op_sel_hi:[0,1]
	v_lshlrev_b64 v[34:35], 9, v[30:31]
	v_pk_mul_f32 v[10:11], v[10:11], v[32:33]
	v_lshl_add_u64 v[34:35], v[16:17], 0, v[34:35]
	v_cvt_pk_bf16_f32 v32, v8, v9
	v_cvt_pk_bf16_f32 v33, v10, v11
	global_store_dwordx2 v[34:35], v[32:33], off
	s_and_saveexec_b64 s[6:7], s[36:37]
	s_cbranch_execz .LBB0_444
	v_ashrrev_i32_e32 v31, 7, v30
	v_and_or_b32 v32, v31, -2, s58
	v_readlane_b32 s0, v238, 54
	v_ashrrev_i32_e32 v33, 31, v32
	v_lshlrev_b64 v[32:33], 18, v[32:33]
	v_add_u32_e32 v31, s0, v15
	v_and_b32_e32 v31, 0xff00, v31
	v_lshl_add_u64 v[32:33], s[10:11], 0, v[32:33]
	v_lshlrev_b32_e32 v164, 2, v31
	v_lshl_add_u64 v[32:33], v[32:33], 0, v[164:165]
	v_lshlrev_b32_e32 v164, 2, v14
	v_lshl_add_u64 v[32:33], v[32:33], 0, v[164:165]
	global_store_dwordx4 v[32:33], v[8:11], off
	s_branch .LBB0_444
